# grid barrier master poll: the 16 arrival-counter loads issued together, one wait, then summed (were load/wait/add one at a time)
# baseline (speedup 1.0000x reference)
; DI unsigned xb_ld(unsigned* p)              { return __hip_atomic_load(p, __ATOMIC_RELAXED, __HIP_MEMORY_SCOPE_AGENT); }
; DI void xcd_barrier_complete(unsigned* bar, unsigned x, unsigned& nloc, unsigned& nx) {
;     ...
;     for (;;) {
;         sum = 0u; cnt = 0u; mine = 0u;
; #pragma unroll
;         for (unsigned j = 0; j < 16; ++j) { const unsigned c = xb_ld(&bar[XB_XCNT(j)]); sum += c; cnt += (c > 0u) ? 1u : 0u; mine = (j == x) ? c : mine; }
;         if (sum == G) break;
;         __builtin_amdgcn_s_sleep(1);
;         if ((++sp & 255u) == 0u) { if (xb_ld(&bar[XB_TMO])) break; if (sp > XB_SPIN_CAP) { atomicAdd(&bar[XB_TMO], 1u); break; } }
;     }
.LBB0_522:
	v_readlane_b32 s4, v246, 7
	v_readlane_b32 s5, v246, 8
	s_mov_b64 s[6:7], -1
	s_nop 3
	global_load_dword v0, v1, s[4:5] sc1
	v_readlane_b32 s4, v246, 9
	v_readlane_b32 s5, v246, 10
	s_waitcnt lgkmcnt(0)
	s_nop 3
	global_load_dword v2, v1, s[4:5] sc1
	v_readlane_b32 s4, v246, 11
	v_readlane_b32 s5, v246, 12
	s_nop 1
	s_nop 2
	global_load_dword v3, v1, s[4:5] sc1
	v_readlane_b32 s4, v246, 13
	v_readlane_b32 s5, v246, 14
	s_nop 1
	s_nop 2
	global_load_dword v4, v1, s[4:5] sc1
	v_readlane_b32 s4, v246, 15
	v_readlane_b32 s5, v246, 16
	s_nop 1
	s_nop 2
	global_load_dword v5, v1, s[4:5] sc1
	v_readlane_b32 s4, v246, 17
	v_readlane_b32 s5, v246, 18
	s_nop 1
	s_nop 2
	global_load_dword v6, v1, s[4:5] sc1
	v_readlane_b32 s4, v246, 19
	v_readlane_b32 s5, v246, 20
	s_nop 1
	s_nop 2
	global_load_dword v7, v1, s[4:5] sc1
	v_readlane_b32 s4, v246, 21
	v_readlane_b32 s5, v246, 22
	s_nop 1
	s_nop 2
	global_load_dword v8, v1, s[4:5] sc1
	v_readlane_b32 s4, v246, 23
	v_readlane_b32 s5, v246, 24
	s_nop 1
	s_nop 2
	global_load_dword v9, v1, s[4:5] sc1
	v_readlane_b32 s4, v246, 25
	v_readlane_b32 s5, v246, 26
	s_nop 1
	s_nop 2
	global_load_dword v10, v1, s[4:5] sc1
	v_readlane_b32 s4, v246, 27
	v_readlane_b32 s5, v246, 28
	s_nop 1
	s_nop 2
	global_load_dword v11, v1, s[4:5] sc1
	v_readlane_b32 s4, v246, 29
	v_readlane_b32 s5, v246, 30
	s_nop 1
	s_nop 2
	global_load_dword v12, v1, s[4:5] sc1
	v_readlane_b32 s4, v246, 31
	v_readlane_b32 s5, v246, 32
	s_nop 1
	s_nop 2
	global_load_dword v13, v1, s[4:5] sc1
	v_readlane_b32 s4, v246, 33
	v_readlane_b32 s5, v246, 34
	s_nop 1
	s_nop 2
	global_load_dword v14, v1, s[4:5] sc1
	v_readlane_b32 s4, v246, 35
	v_readlane_b32 s5, v246, 36
	s_nop 1
	s_nop 2
	global_load_dword v15, v1, s[4:5] sc1
	v_readlane_b32 s4, v246, 37
	v_readlane_b32 s5, v246, 38
	s_nop 1
	s_nop 2
	global_load_dword v16, v1, s[4:5] sc1
	s_mov_b64 s[4:5], -1
	s_nop 1
	s_waitcnt vmcnt(0)
	v_add_u32_e32 v17, v2, v0
	v_add_u32_e32 v17, v17, v3
	v_add_u32_e32 v17, v17, v4
	v_add_u32_e32 v17, v17, v5
	v_add_u32_e32 v17, v17, v6
	v_add_u32_e32 v17, v17, v7
	v_add_u32_e32 v17, v17, v8
	v_add_u32_e32 v17, v17, v9
	v_add_u32_e32 v17, v17, v10
	v_add_u32_e32 v17, v17, v11
	v_add_u32_e32 v17, v17, v12
	v_add_u32_e32 v17, v17, v13
	v_add_u32_e32 v17, v17, v14
	v_add_u32_e32 v17, v17, v15
	v_add_u32_e32 v17, v17, v16
	v_cmp_eq_u32_e32 vcc, s2, v17
	s_cbranch_vccnz .LBB0_521
	s_and_b32 s4, s10, 0xff
	s_cmp_eq_u32 s4, 0
	s_mov_b64 s[4:5], -1
	s_mov_b64 s[8:9], -1
	s_sleep 1
	s_cbranch_scc0 .LBB0_526
	v_readlane_b32 s4, v246, 5
	v_readlane_b32 s5, v246, 6
	s_nop 4
	global_load_dword v17, v1, s[4:5] sc1
	s_waitcnt vmcnt(0)
	v_cmp_eq_u32_e32 vcc, 0, v17
	s_cbranch_vccnz .LBB0_528
	s_mov_b64 s[8:9], 0
	s_mov_b64 s[4:5], -1
